# attention Q prologue: volatile uncached flat reloads of Q replaced by paired cached global loads
# speedup vs baseline: 1.0029x; 1.0002x over previous
.LBB0_1145:
	s_cmpk_gt_i32 s67, 0x1ff
	s_mov_b64 s[6:7], -1
	s_cbranch_scc0 .LBB0_1160
	s_add_i32 s20, s67, 0xfffffe00
	s_lshl_b32 s0, s20, 4
	s_mov_b32 s13, s15
	s_and_b32 s14, s0, 0x7fffff00
	s_lshl_b64 s[6:7], s[12:13], 16
	s_and_b32 s13, s67, 15
	s_mul_i32 s1, s14, 0x1800
	s_mul_hi_u32 s0, s14, 0x1800
	s_add_u32 s1, s76, s1
	s_addc_u32 s4, s77, s0
	s_mul_i32 s0, s13, 0x180
	s_add_u32 s0, s1, s0
	s_waitcnt vmcnt(0)
	v_mov_b32_e32 v45, v204
	s_addc_u32 s1, s4, 0
	v_mov_b64_e32 v[0:1], s[0:1]
	v_ashrrev_i32_e32 v8, 1, v45
	v_bfe_u32 v183, v45, 5, 1
	v_bfi_b32 v2, s31, v8, v45
	v_mad_i64_i32 v[0:1], s[0:1], v2, s29, v[0:1]
	v_lshlrev_b32_e32 v166, 4, v183
	v_mov_b32_e32 v167, v165
	v_lshl_add_u64 v[42:43], v[0:1], 0, v[166:167]
	s_waitcnt lgkmcnt(0)
	s_barrier
	global_load_dwordx4 v[4:7], v[42:43], off
	global_load_dwordx4 v[10:13], v[42:43], off offset:32
	global_load_dwordx4 v[18:21], v[42:43], off offset:64
	global_load_dwordx4 v[22:25], v[42:43], off offset:96
	global_load_dwordx4 v[26:29], v[42:43], off offset:128
	global_load_dwordx4 v[30:33], v[42:43], off offset:160
	global_load_dwordx4 v[34:37], v[42:43], off offset:192
	global_load_dwordx4 v[38:41], v[42:43], off offset:224
	global_load_dwordx4 v[46:49], v[42:43], off offset:256
	global_load_dwordx4 v[0:3], v[42:43], off offset:288
	global_load_dwordx4 v[14:17], v[42:43], off offset:320
	v_cmp_lt_i32_e32 vcc, v180, v181
	v_and_b32_e32 v168, 0xffffffe0, v8
	s_mul_i32 s1, s20, 0x18000
	s_mov_b32 s21, s15
	s_mul_hi_u32 s0, s20, 0x18000
	s_add_u32 s4, s2, s1
	s_addc_u32 s5, s3, s0
	s_lshl_b64 s[20:21], s[20:21], 16
	s_add_u32 s20, s24, s20
	s_addc_u32 s21, s25, s21
	s_cmp_lg_u32 16, -1
	s_mul_i32 s68, s12, 0x18000
	s_mul_hi_u32 s23, s12, 0x18000
	v_and_b32_e32 v164, 31, v45
	s_mov_b32 s22, 0
	v_mul_u32_u24_e32 v188, 0x180, v164
	v_mov_b32_e32 v207, 0
	v_mov_b32_e32 v186, 0xf149f2ca
	s_waitcnt vmcnt(10)
	v_lshlrev_b32_e32 v9, 16, v4
	v_and_b32_e32 v4, 0xffff0000, v4
	v_mul_f32_e32 v71, v4, v4
	v_lshlrev_b32_e32 v44, 16, v5
	v_fmac_f32_e32 v71, v9, v9
	v_and_b32_e32 v5, 0xffff0000, v5
	v_fmac_f32_e32 v71, v44, v44
	v_lshlrev_b32_e32 v50, 16, v6
	v_fmac_f32_e32 v71, v5, v5
	v_and_b32_e32 v6, 0xffff0000, v6
	v_fmac_f32_e32 v71, v50, v50
	v_lshlrev_b32_e32 v51, 16, v7
	v_fmac_f32_e32 v71, v6, v6
	v_and_b32_e32 v7, 0xffff0000, v7
	v_fmac_f32_e32 v71, v51, v51
	s_waitcnt vmcnt(9)
	v_lshlrev_b32_e32 v52, 16, v10
	v_fmac_f32_e32 v71, v7, v7
	v_and_b32_e32 v10, 0xffff0000, v10
	v_fmac_f32_e32 v71, v52, v52
	v_lshlrev_b32_e32 v53, 16, v11
	v_fmac_f32_e32 v71, v10, v10
	v_and_b32_e32 v11, 0xffff0000, v11
	v_fmac_f32_e32 v71, v53, v53
	v_lshlrev_b32_e32 v54, 16, v12
	v_fmac_f32_e32 v71, v11, v11
	v_and_b32_e32 v12, 0xffff0000, v12
	v_fmac_f32_e32 v71, v54, v54
	v_lshlrev_b32_e32 v55, 16, v13
	v_fmac_f32_e32 v71, v12, v12
	v_and_b32_e32 v13, 0xffff0000, v13
	v_fmac_f32_e32 v71, v55, v55
	s_waitcnt vmcnt(8)
	v_lshlrev_b32_e32 v56, 16, v18
	v_fmac_f32_e32 v71, v13, v13
	v_and_b32_e32 v18, 0xffff0000, v18
	v_fmac_f32_e32 v71, v56, v56
	v_lshlrev_b32_e32 v57, 16, v19
	v_fmac_f32_e32 v71, v18, v18
	v_and_b32_e32 v19, 0xffff0000, v19
	v_fmac_f32_e32 v71, v57, v57
	v_lshlrev_b32_e32 v58, 16, v20
	v_fmac_f32_e32 v71, v19, v19
	v_and_b32_e32 v20, 0xffff0000, v20
	v_fmac_f32_e32 v71, v58, v58
	v_lshlrev_b32_e32 v59, 16, v21
	v_fmac_f32_e32 v71, v20, v20
	v_and_b32_e32 v21, 0xffff0000, v21
	v_fmac_f32_e32 v71, v59, v59
	s_waitcnt vmcnt(7)
	v_lshlrev_b32_e32 v60, 16, v22
	v_fmac_f32_e32 v71, v21, v21
	v_and_b32_e32 v22, 0xffff0000, v22
	v_fmac_f32_e32 v71, v60, v60
	v_lshlrev_b32_e32 v61, 16, v23
	v_fmac_f32_e32 v71, v22, v22
	v_and_b32_e32 v23, 0xffff0000, v23
	v_fmac_f32_e32 v71, v61, v61
	v_lshlrev_b32_e32 v62, 16, v24
	v_fmac_f32_e32 v71, v23, v23
	v_and_b32_e32 v24, 0xffff0000, v24
	v_fmac_f32_e32 v71, v62, v62
	v_lshlrev_b32_e32 v63, 16, v25
	v_fmac_f32_e32 v71, v24, v24
	v_and_b32_e32 v25, 0xffff0000, v25
	v_fmac_f32_e32 v71, v63, v63
	s_waitcnt vmcnt(6)
	v_lshlrev_b32_e32 v64, 16, v26
	v_fmac_f32_e32 v71, v25, v25
	v_and_b32_e32 v26, 0xffff0000, v26
	v_fmac_f32_e32 v71, v64, v64
	v_lshlrev_b32_e32 v65, 16, v27
	v_fmac_f32_e32 v71, v26, v26
	v_and_b32_e32 v27, 0xffff0000, v27
	v_fmac_f32_e32 v71, v65, v65
	v_lshlrev_b32_e32 v66, 16, v28
	v_fmac_f32_e32 v71, v27, v27
	v_and_b32_e32 v28, 0xffff0000, v28
	v_fmac_f32_e32 v71, v66, v66
	v_lshlrev_b32_e32 v67, 16, v29
	v_fmac_f32_e32 v71, v28, v28
	v_and_b32_e32 v29, 0xffff0000, v29
	v_fmac_f32_e32 v71, v67, v67
	s_waitcnt vmcnt(5)
	v_lshlrev_b32_e32 v68, 16, v30
	v_fmac_f32_e32 v71, v29, v29
	v_and_b32_e32 v30, 0xffff0000, v30
	v_fmac_f32_e32 v71, v68, v68
	v_lshlrev_b32_e32 v69, 16, v31
	v_fmac_f32_e32 v71, v30, v30
	v_and_b32_e32 v31, 0xffff0000, v31
	v_fmac_f32_e32 v71, v69, v69
	v_lshlrev_b32_e32 v70, 16, v32
	v_fmac_f32_e32 v71, v31, v31
	v_fmac_f32_e32 v71, v70, v70
	v_and_b32_e32 v4, 0xffff0000, v32
	v_fmac_f32_e32 v71, v4, v4
	v_lshlrev_b32_e32 v4, 16, v33
	global_load_dwordx4 v[18:21], v[42:43], off offset:352
	v_fmac_f32_e32 v71, v4, v4
	v_and_b32_e32 v4, 0xffff0000, v33
	v_fmac_f32_e32 v71, v4, v4
	s_waitcnt vmcnt(5)
	v_lshlrev_b32_e32 v4, 16, v34
	v_fmac_f32_e32 v71, v4, v4
	v_and_b32_e32 v4, 0xffff0000, v34
	v_fmac_f32_e32 v71, v4, v4
	v_lshlrev_b32_e32 v4, 16, v35
	v_fmac_f32_e32 v71, v4, v4
	v_and_b32_e32 v4, 0xffff0000, v35
	v_fmac_f32_e32 v71, v4, v4
	v_lshlrev_b32_e32 v4, 16, v36
	v_fmac_f32_e32 v71, v4, v4
	v_and_b32_e32 v4, 0xffff0000, v36
	v_fmac_f32_e32 v71, v4, v4
	v_lshlrev_b32_e32 v4, 16, v37
	v_fmac_f32_e32 v71, v4, v4
	v_and_b32_e32 v4, 0xffff0000, v37
	v_fmac_f32_e32 v71, v4, v4
	s_waitcnt vmcnt(4)
	v_lshlrev_b32_e32 v4, 16, v38
	v_fmac_f32_e32 v71, v4, v4
	v_and_b32_e32 v4, 0xffff0000, v38
	v_fmac_f32_e32 v71, v4, v4
	v_lshlrev_b32_e32 v4, 16, v39
	v_fmac_f32_e32 v71, v4, v4
	v_and_b32_e32 v4, 0xffff0000, v39
	v_fmac_f32_e32 v71, v4, v4
	v_lshlrev_b32_e32 v4, 16, v40
	v_fmac_f32_e32 v71, v4, v4
	v_and_b32_e32 v4, 0xffff0000, v40
	v_fmac_f32_e32 v71, v4, v4
	v_lshlrev_b32_e32 v4, 16, v41
	v_fmac_f32_e32 v71, v4, v4
	v_and_b32_e32 v4, 0xffff0000, v41
	v_fmac_f32_e32 v71, v4, v4
	s_waitcnt vmcnt(3)
	v_lshlrev_b32_e32 v4, 16, v46
	v_fmac_f32_e32 v71, v4, v4
	v_and_b32_e32 v4, 0xffff0000, v46
	v_fmac_f32_e32 v71, v4, v4
	v_lshlrev_b32_e32 v4, 16, v47
	v_fmac_f32_e32 v71, v4, v4
	v_and_b32_e32 v4, 0xffff0000, v47
	v_fmac_f32_e32 v71, v4, v4
	v_lshlrev_b32_e32 v4, 16, v48
	v_fmac_f32_e32 v71, v4, v4
	v_and_b32_e32 v4, 0xffff0000, v48
	v_fmac_f32_e32 v71, v4, v4
	v_lshlrev_b32_e32 v4, 16, v49
	v_fmac_f32_e32 v71, v4, v4
	v_and_b32_e32 v4, 0xffff0000, v49
	v_fmac_f32_e32 v71, v4, v4
	s_waitcnt vmcnt(2)
	v_lshlrev_b32_e32 v4, 16, v0
	v_fmac_f32_e32 v71, v4, v4
	global_load_dwordx4 v[10:13], v[42:43], off
	global_load_dwordx4 v[4:7], v[42:43], off offset:32
	s_waitcnt vmcnt(0)
	v_and_b32_e32 v47, 32, v45
	global_load_dwordx4 v[22:25], v47, s[10:11] offset:16
	global_load_dwordx4 v[30:33], v47, s[10:11]
	global_load_dwordx4 v[34:37], v47, s[10:11] offset:80
	global_load_dwordx4 v[48:51], v47, s[10:11] offset:64
	v_and_b32_e32 v0, 0xffff0000, v0
	v_fmac_f32_e32 v71, v0, v0
	v_lshlrev_b32_e32 v0, 16, v1
	v_fmac_f32_e32 v71, v0, v0
	v_and_b32_e32 v0, 0xffff0000, v1
	v_fmac_f32_e32 v71, v0, v0
	v_lshlrev_b32_e32 v0, 16, v2
	v_fmac_f32_e32 v71, v0, v0
	v_and_b32_e32 v0, 0xffff0000, v2
	v_fmac_f32_e32 v71, v0, v0
	v_lshlrev_b32_e32 v0, 16, v3
	v_fmac_f32_e32 v71, v0, v0
	v_and_b32_e32 v0, 0xffff0000, v3
	v_fmac_f32_e32 v71, v0, v0
	v_lshlrev_b32_e32 v0, 16, v14
	v_fmac_f32_e32 v71, v0, v0
	v_and_b32_e32 v0, 0xffff0000, v14
	v_fmac_f32_e32 v71, v0, v0
	v_lshlrev_b32_e32 v0, 16, v15
	v_fmac_f32_e32 v71, v0, v0
	v_and_b32_e32 v0, 0xffff0000, v15
	v_fmac_f32_e32 v71, v0, v0
	v_lshlrev_b32_e32 v0, 16, v16
	v_fmac_f32_e32 v71, v0, v0
	v_and_b32_e32 v0, 0xffff0000, v16
	v_fmac_f32_e32 v71, v0, v0
	v_and_b32_e32 v1, 0xffff0000, v17
	v_lshlrev_b32_e32 v0, 16, v17
	v_pk_mul_f32 v[0:1], v[0:1], v[0:1]
	v_and_b32_e32 v46, 63, v45
	v_add_f32_e32 v0, v0, v71
	v_add_f32_e32 v2, v1, v0
	v_and_b32_e32 v1, 0xffff0000, v18
	v_lshlrev_b32_e32 v0, 16, v18
	v_pk_mul_f32 v[0:1], v[0:1], v[0:1]
	v_lshlrev_b32_e32 v18, 16, v20
	v_add_f32_e32 v0, v0, v2
	v_add_f32_e32 v2, v1, v0
	v_and_b32_e32 v1, 0xffff0000, v19
	v_lshlrev_b32_e32 v0, 16, v19
	v_pk_mul_f32 v[0:1], v[0:1], v[0:1]
	v_and_b32_e32 v19, 0xffff0000, v20
	v_add_f32_e32 v0, v0, v2
	v_add_f32_e32 v9, v1, v0
	v_pk_mul_f32 v[18:19], v[18:19], v[18:19]
	global_load_dwordx4 v[14:17], v[42:43], off offset:64
	global_load_dwordx4 v[0:3], v[42:43], off offset:96
	s_waitcnt vmcnt(0)
	global_load_dwordx4 v[26:29], v47, s[10:11] offset:144
	global_load_dwordx4 v[52:55], v47, s[10:11] offset:128
	v_add_f32_e32 v9, v18, v9
	v_add_f32_e32 v9, v19, v9
	v_and_b32_e32 v19, 0xffff0000, v21
	v_lshlrev_b32_e32 v18, 16, v21
	v_pk_mul_f32 v[18:19], v[18:19], v[18:19]
	global_load_dwordx4 v[38:41], v47, s[10:11] offset:208
	global_load_dwordx4 v[56:59], v47, s[10:11] offset:192
	v_add_f32_e32 v9, v18, v9
	v_cndmask_b32_e32 v18, v179, v180, vcc
	v_add_f32_e32 v9, v19, v9
	v_lshlrev_b32_e32 v18, 2, v18
	ds_bpermute_b32 v18, v18, v9
	v_and_b32_e32 v19, 0x3fffffc0, v45
	v_lshl_add_u32 v167, v19, 2, s66
	v_lshl_add_u32 v184, v164, 2, v167
	v_add_u32_e32 v169, v167, v166
	s_waitcnt lgkmcnt(0)
	v_add_f32_e32 v9, v9, v18
	v_fmamk_f32 v9, v9, 0x3baaaaab, v178
	v_mul_f32_e32 v18, 0x4b800000, v9
	v_cmp_gt_f32_e32 vcc, s33, v9
	v_and_b32_e32 v75, 0xffff0000, v12
	s_nop 0
	v_cndmask_b32_e32 v9, v9, v18, vcc
	v_rsq_f32_e32 v9, v9
	v_lshlrev_b32_e32 v74, 16, v12
	v_mul_f32_e32 v8, 0x45800000, v9
	v_cndmask_b32_e32 v44, v9, v8, vcc
	v_and_b32_e32 v9, 0xffff0000, v10
	v_lshlrev_b32_e32 v8, 16, v10
	v_pk_mul_f32 v[8:9], v[44:45], v[8:9] op_sel_hi:[0,1]
	v_pk_mul_f32 v[68:69], v[30:31], v[8:9]
	v_and_b32_e32 v9, 0xffff0000, v4
	v_lshlrev_b32_e32 v8, 16, v4
	v_pk_mul_f32 v[8:9], v[44:45], v[8:9] op_sel_hi:[0,1]
	v_pk_mul_f32 v[70:71], v[48:49], v[8:9]
	v_and_b32_e32 v9, 0xffff0000, v11
	v_lshlrev_b32_e32 v8, 16, v11
	v_pk_mul_f32 v[8:9], v[44:45], v[8:9] op_sel_hi:[0,1]
	v_pk_mul_f32 v[72:73], v[32:33], v[8:9]
	global_load_dwordx4 v[18:21], v[42:43], off offset:128
	global_load_dwordx4 v[8:11], v[42:43], off offset:160
	s_waitcnt vmcnt(0)
	global_load_dwordx4 v[30:33], v47, s[10:11] offset:272
	global_load_dwordx4 v[60:63], v47, s[10:11] offset:256
	v_and_b32_e32 v49, 0xffff0000, v5
	v_lshlrev_b32_e32 v48, 16, v5
	v_pk_mul_f32 v[4:5], v[44:45], v[48:49] op_sel_hi:[0,1]
	v_pk_mul_f32 v[4:5], v[50:51], v[4:5]
	global_load_dwordx4 v[48:51], v47, s[10:11] offset:336
	global_load_dwordx4 v[64:67], v47, s[10:11] offset:320
	v_cvt_pk_bf16_f32 v97, v4, v5
	v_pk_mul_f32 v[74:75], v[44:45], v[74:75] op_sel_hi:[0,1]
	v_pk_mul_f32 v[22:23], v[22:23], v[74:75]
	v_and_b32_e32 v75, 0xffff0000, v6
	v_lshlrev_b32_e32 v74, 16, v6
	v_cvt_pk_bf16_f32 v101, v72, v73
	v_pk_mul_f32 v[74:75], v[44:45], v[74:75] op_sel_hi:[0,1]
	v_pk_mul_f32 v[34:35], v[34:35], v[74:75]
	v_and_b32_e32 v75, 0xffff0000, v13
	v_lshlrev_b32_e32 v74, 16, v13
	v_pk_mul_f32 v[12:13], v[44:45], v[74:75] op_sel_hi:[0,1]
	v_pk_mul_f32 v[12:13], v[24:25], v[12:13]
	v_and_b32_e32 v25, 0xffff0000, v7
	v_lshlrev_b32_e32 v24, 16, v7
	v_pk_mul_f32 v[6:7], v[44:45], v[24:25] op_sel_hi:[0,1]
	v_pk_mul_f32 v[6:7], v[36:37], v[6:7]
	v_cvt_pk_bf16_f32 v102, v22, v23
	v_cvt_pk_bf16_f32 v103, v12, v13
	v_cvt_pk_bf16_f32 v98, v34, v35
	v_cvt_pk_bf16_f32 v99, v6, v7
	v_cvt_pk_bf16_f32 v100, v68, v69
	v_and_b32_e32 v5, 0xffff0000, v14
	v_lshlrev_b32_e32 v4, 16, v14
	v_pk_mul_f32 v[4:5], v[44:45], v[4:5] op_sel_hi:[0,1]
	v_and_b32_e32 v77, 0xffff0000, v1
	v_lshlrev_b32_e32 v76, 16, v1
	v_pk_mul_f32 v[72:73], v[52:53], v[4:5]
	v_and_b32_e32 v5, 0xffff0000, v0
	v_lshlrev_b32_e32 v4, 16, v0
	v_pk_mul_f32 v[0:1], v[44:45], v[76:77] op_sel_hi:[0,1]
	v_pk_mul_f32 v[0:1], v[58:59], v[0:1]
	v_and_b32_e32 v59, 0xffff0000, v16
	v_lshlrev_b32_e32 v58, 16, v16
	v_pk_mul_f32 v[58:59], v[44:45], v[58:59] op_sel_hi:[0,1]
	v_pk_mul_f32 v[26:27], v[26:27], v[58:59]
	v_and_b32_e32 v59, 0xffff0000, v2
	v_lshlrev_b32_e32 v58, 16, v2
	v_pk_mul_f32 v[4:5], v[44:45], v[4:5] op_sel_hi:[0,1]
	v_pk_mul_f32 v[58:59], v[44:45], v[58:59] op_sel_hi:[0,1]
	v_pk_mul_f32 v[56:57], v[56:57], v[4:5]
	v_and_b32_e32 v5, 0xffff0000, v15
	v_lshlrev_b32_e32 v4, 16, v15
	v_pk_mul_f32 v[38:39], v[38:39], v[58:59]
	v_and_b32_e32 v59, 0xffff0000, v17
	v_lshlrev_b32_e32 v58, 16, v17
	v_pk_mul_f32 v[4:5], v[44:45], v[4:5] op_sel_hi:[0,1]
	v_pk_mul_f32 v[16:17], v[44:45], v[58:59] op_sel_hi:[0,1]
	v_pk_mul_f32 v[74:75], v[54:55], v[4:5]
	global_load_dwordx4 v[4:7], v[42:43], off offset:192
	global_load_dwordx4 v[12:15], v[42:43], off offset:224
	s_waitcnt vmcnt(0)
	global_load_dwordx4 v[22:25], v47, s[10:11] offset:400
	global_load_dwordx4 v[34:37], v47, s[10:11] offset:384
	v_pk_mul_f32 v[16:17], v[28:29], v[16:17]
	v_and_b32_e32 v29, 0xffff0000, v3
	v_lshlrev_b32_e32 v28, 16, v3
	v_pk_mul_f32 v[2:3], v[44:45], v[28:29] op_sel_hi:[0,1]
	v_cvt_pk_bf16_f32 v105, v0, v1
	v_pk_mul_f32 v[2:3], v[40:41], v[2:3]
	v_cvt_pk_bf16_f32 v96, v70, v71
	global_load_dwordx4 v[52:55], v47, s[10:11] offset:464
	global_load_dwordx4 v[68:71], v47, s[10:11] offset:448
	v_cvt_pk_bf16_f32 v110, v26, v27
	v_cvt_pk_bf16_f32 v111, v16, v17
	v_cvt_pk_bf16_f32 v104, v56, v57
	v_cvt_pk_bf16_f32 v106, v38, v39
	v_cvt_pk_bf16_f32 v107, v2, v3
	v_cvt_pk_bf16_f32 v108, v72, v73
	v_cvt_pk_bf16_f32 v109, v74, v75
	s_waitcnt lgkmcnt(0)
	v_and_b32_e32 v1, 0xffff0000, v18
	v_lshlrev_b32_e32 v0, 16, v18
	v_pk_mul_f32 v[0:1], v[44:45], v[0:1] op_sel_hi:[0,1]
	v_pk_mul_f32 v[16:17], v[60:61], v[0:1]
	global_load_dwordx4 v[0:3], v[42:43], off offset:256
	global_load_dwordx4 v[26:29], v[42:43], off offset:288
	s_waitcnt vmcnt(0)
	global_load_dwordx4 v[38:41], v47, s[10:11] offset:528
	global_load_dwordx4 v[56:59], v47, s[10:11] offset:512
	global_load_dwordx4 v[72:75], v47, s[10:11] offset:592
	global_load_dwordx4 v[76:79], v47, s[10:11] offset:576
	v_and_b32_e32 v61, 0xffff0000, v8
	v_lshlrev_b32_e32 v60, 16, v8
	v_pk_mul_f32 v[60:61], v[44:45], v[60:61] op_sel_hi:[0,1]
	v_pk_mul_f32 v[60:61], v[64:65], v[60:61]
	v_and_b32_e32 v65, 0xffff0000, v19
	v_lshlrev_b32_e32 v64, 16, v19
	v_pk_mul_f32 v[18:19], v[44:45], v[64:65] op_sel_hi:[0,1]
	v_pk_mul_f32 v[18:19], v[62:63], v[18:19]
	v_and_b32_e32 v63, 0xffff0000, v9
	v_lshlrev_b32_e32 v62, 16, v9
	v_pk_mul_f32 v[8:9], v[44:45], v[62:63] op_sel_hi:[0,1]
	v_and_b32_e32 v63, 0xffff0000, v20
	v_lshlrev_b32_e32 v62, 16, v20
	v_pk_mul_f32 v[62:63], v[44:45], v[62:63] op_sel_hi:[0,1]
	v_pk_mul_f32 v[30:31], v[30:31], v[62:63]
	v_and_b32_e32 v63, 0xffff0000, v10
	v_lshlrev_b32_e32 v62, 16, v10
	v_pk_mul_f32 v[62:63], v[44:45], v[62:63] op_sel_hi:[0,1]
	v_pk_mul_f32 v[48:49], v[48:49], v[62:63]
	v_and_b32_e32 v63, 0xffff0000, v21
	v_lshlrev_b32_e32 v62, 16, v21
	v_pk_mul_f32 v[8:9], v[66:67], v[8:9]
	v_pk_mul_f32 v[20:21], v[44:45], v[62:63] op_sel_hi:[0,1]
	v_cvt_pk_bf16_f32 v116, v16, v17
	v_pk_mul_f32 v[20:21], v[32:33], v[20:21]
	v_and_b32_e32 v33, 0xffff0000, v11
	v_lshlrev_b32_e32 v32, 16, v11
	v_cvt_pk_bf16_f32 v113, v8, v9
	v_pk_mul_f32 v[10:11], v[44:45], v[32:33] op_sel_hi:[0,1]
	v_pk_mul_f32 v[10:11], v[50:51], v[10:11]
	v_cvt_pk_bf16_f32 v119, v20, v21
	v_cvt_pk_bf16_f32 v115, v10, v11
	v_cvt_pk_bf16_f32 v118, v30, v31
	v_cvt_pk_bf16_f32 v117, v18, v19
	v_cvt_pk_bf16_f32 v114, v48, v49
	v_ashrrev_i32_e32 v48, 4, v45
	v_add_u32_e32 v50, 32, v48
	v_ashrrev_i32_e32 v49, 31, v48
	v_ashrrev_i32_e32 v51, 31, v50
	v_cvt_pk_bf16_f32 v112, v60, v61
	v_and_b32_e32 v17, 0xffff0000, v5
	v_lshlrev_b32_e32 v16, 16, v5
	v_and_b32_e32 v9, 0xffff0000, v4
	v_lshlrev_b32_e32 v8, 16, v4
	v_pk_mul_f32 v[4:5], v[44:45], v[16:17] op_sel_hi:[0,1]
	v_pk_mul_f32 v[4:5], v[36:37], v[4:5]
	v_and_b32_e32 v17, 0xffff0000, v13
	v_lshlrev_b32_e32 v16, 16, v13
	v_and_b32_e32 v21, 0xffff0000, v7
	v_lshlrev_b32_e32 v20, 16, v7
	v_cvt_pk_bf16_f32 v125, v4, v5
	v_and_b32_e32 v11, 0xffff0000, v12
	v_lshlrev_b32_e32 v10, 16, v12
	v_pk_mul_f32 v[12:13], v[44:45], v[16:17] op_sel_hi:[0,1]
	v_and_b32_e32 v17, 0xffff0000, v6
	v_lshlrev_b32_e32 v16, 16, v6
	v_pk_mul_f32 v[6:7], v[44:45], v[20:21] op_sel_hi:[0,1]
	v_pk_mul_f32 v[6:7], v[24:25], v[6:7]
	v_and_b32_e32 v19, 0xffff0000, v14
	v_lshlrev_b32_e32 v18, 16, v14
	v_and_b32_e32 v21, 0xffff0000, v15
	v_lshlrev_b32_e32 v20, 16, v15
	v_pk_mul_f32 v[8:9], v[44:45], v[8:9] op_sel_hi:[0,1]
	v_pk_mul_f32 v[10:11], v[44:45], v[10:11] op_sel_hi:[0,1]
	v_pk_mul_f32 v[16:17], v[44:45], v[16:17] op_sel_hi:[0,1]
	v_pk_mul_f32 v[18:19], v[44:45], v[18:19] op_sel_hi:[0,1]
	v_pk_mul_f32 v[14:15], v[44:45], v[20:21] op_sel_hi:[0,1]
	s_waitcnt lgkmcnt(0)
	v_and_b32_e32 v5, 0xffff0000, v0
	v_lshlrev_b32_e32 v4, 16, v0
	v_pk_mul_f32 v[4:5], v[44:45], v[4:5] op_sel_hi:[0,1]
	s_waitcnt vmcnt(2)
	v_pk_mul_f32 v[24:25], v[56:57], v[4:5]
	v_and_b32_e32 v5, 0xffff0000, v26
	v_lshlrev_b32_e32 v4, 16, v26
	v_pk_mul_f32 v[4:5], v[44:45], v[4:5] op_sel_hi:[0,1]
	s_waitcnt vmcnt(0)
	v_pk_mul_f32 v[30:31], v[76:77], v[4:5]
	v_and_b32_e32 v5, 0xffff0000, v1
	v_lshlrev_b32_e32 v4, 16, v1
	v_pk_mul_f32 v[0:1], v[44:45], v[4:5] op_sel_hi:[0,1]
	v_pk_mul_f32 v[32:33], v[58:59], v[0:1]
	v_and_b32_e32 v1, 0xffff0000, v27
	v_lshlrev_b32_e32 v0, 16, v27
	v_pk_mul_f32 v[0:1], v[44:45], v[0:1] op_sel_hi:[0,1]
	v_pk_mul_f32 v[26:27], v[78:79], v[0:1]
	v_and_b32_e32 v1, 0xffff0000, v2
	v_lshlrev_b32_e32 v0, 16, v2
	v_pk_mul_f32 v[8:9], v[34:35], v[8:9]
	v_pk_mul_f32 v[10:11], v[68:69], v[10:11]
	v_pk_mul_f32 v[12:13], v[70:71], v[12:13]
	v_pk_mul_f32 v[16:17], v[22:23], v[16:17]
	v_pk_mul_f32 v[18:19], v[52:53], v[18:19]
	v_pk_mul_f32 v[14:15], v[54:55], v[14:15]
	v_pk_mul_f32 v[0:1], v[44:45], v[0:1] op_sel_hi:[0,1]
	v_cvt_pk_bf16_f32 v124, v8, v9
	v_cvt_pk_bf16_f32 v126, v16, v17
	v_cvt_pk_bf16_f32 v127, v6, v7
	v_cvt_pk_bf16_f32 v120, v10, v11
	v_cvt_pk_bf16_f32 v121, v12, v13
	v_cvt_pk_bf16_f32 v122, v18, v19
	v_cvt_pk_bf16_f32 v123, v14, v15
	v_pk_mul_f32 v[34:35], v[38:39], v[0:1]
	v_and_b32_e32 v1, 0xffff0000, v28
	v_lshlrev_b32_e32 v0, 16, v28
	global_load_dwordx4 v[4:7], v[42:43], off offset:320
	global_load_dwordx4 v[8:11], v[42:43], off offset:352
	s_waitcnt vmcnt(0)
	global_load_dwordx4 v[12:15], v47, s[10:11] offset:656
	global_load_dwordx4 v[16:19], v47, s[10:11] offset:640
	v_pk_mul_f32 v[0:1], v[44:45], v[0:1] op_sel_hi:[0,1]
	v_pk_mul_f32 v[36:37], v[72:73], v[0:1]
	v_and_b32_e32 v39, 0xffff0000, v3
	v_lshlrev_b32_e32 v38, 16, v3
	global_load_dwordx4 v[0:3], v47, s[10:11] offset:720
	global_load_dwordx4 v[20:23], v47, s[10:11] offset:704
	v_pk_mul_f32 v[38:39], v[44:45], v[38:39] op_sel_hi:[0,1]
	v_pk_mul_f32 v[38:39], v[40:41], v[38:39]
	v_and_b32_e32 v41, 0xffff0000, v29
	v_lshlrev_b32_e32 v40, 16, v29
	v_pk_mul_f32 v[28:29], v[44:45], v[40:41] op_sel_hi:[0,1]
	v_pk_mul_f32 v[28:29], v[74:75], v[28:29]
	v_cvt_pk_bf16_f32 v129, v26, v27
	v_mul_hi_i32 v27, v45, s34
	v_cvt_pk_bf16_f32 v131, v28, v29
	v_lshrrev_b32_e32 v28, 31, v27
	v_ashrrev_i32_e32 v27, 2, v27
	v_add_u32_e32 v62, v27, v28
	v_cvt_pk_bf16_f32 v132, v24, v25
	v_add_u32_e32 v24, 0x200, v45
	v_mul_lo_u32 v27, v62, 24
	v_sub_u32_e32 v63, v45, v27
	v_mul_hi_i32 v27, v24, s34
	v_lshrrev_b32_e32 v28, 31, v27
	v_ashrrev_i32_e32 v27, 2, v27
	v_add_u32_e32 v64, v27, v28
	v_add_u32_e32 v25, 0x400, v45
	v_mul_lo_u32 v27, v64, 24
	v_sub_u32_e32 v65, v24, v27
	v_mul_hi_i32 v24, v25, s34
	v_lshrrev_b32_e32 v27, 31, v24
	v_ashrrev_i32_e32 v24, 2, v24
	v_lshlrev_b32_e32 v47, 3, v45
	v_add_u32_e32 v66, v24, v27
	v_and_b32_e32 v26, 0x78, v47
	v_mul_lo_u32 v24, v66, 24
	v_lshlrev_b64 v[52:53], 8, v[48:49]
	v_lshlrev_b64 v[28:29], 8, v[50:51]
	v_sub_u32_e32 v67, v25, v24
	v_lshl_add_u64 v[24:25], s[20:21], 0, v[52:53]
	v_lshlrev_b32_e32 v26, 1, v26
	v_mov_b32_e32 v27, v165
	v_lshl_add_u64 v[28:29], s[20:21], 0, v[28:29]
	v_cvt_pk_bf16_f32 v134, v34, v35
	v_lshl_add_u64 v[24:25], v[24:25], 0, v[26:27]
	v_lshl_add_u64 v[28:29], v[28:29], 0, v[26:27]
	v_lshlrev_b32_e32 v34, 3, v63
	v_cvt_pk_bf16_f32 v128, v30, v31
	global_load_dwordx4 v[24:27], v[24:25], off
	s_nop 0
	global_load_dwordx4 v[28:31], v[28:29], off
	v_mov_b64_e32 v[40:41], s[4:5]
	v_ashrrev_i32_e32 v35, 31, v34
	v_cvt_pk_bf16_f32 v133, v32, v33
	v_mad_i64_i32 v[32:33], s[0:1], v62, s30, v[40:41]
	v_lshlrev_b64 v[54:55], 1, v[34:35]
	v_cvt_pk_bf16_f32 v135, v38, v39
	v_lshl_add_u64 v[32:33], v[32:33], 0, v[54:55]
	v_lshlrev_b32_e32 v38, 3, v65
	global_load_dwordx4 v[32:35], v[32:33], off
	v_ashrrev_i32_e32 v39, 31, v38
	v_cvt_pk_bf16_f32 v130, v36, v37
	v_mad_i64_i32 v[36:37], s[0:1], v64, s30, v[40:41]
	v_lshlrev_b64 v[56:57], 1, v[38:39]
	v_lshl_add_u64 v[36:37], v[36:37], 0, v[56:57]
	v_lshlrev_b32_e32 v42, 3, v67
	global_load_dwordx4 v[36:39], v[36:37], off
	v_ashrrev_i32_e32 v43, 31, v42
	v_mad_i64_i32 v[40:41], s[0:1], v66, s30, v[40:41]
	v_lshlrev_b64 v[58:59], 1, v[42:43]
	v_lshl_add_u64 v[40:41], v[40:41], 0, v[58:59]
	global_load_dwordx4 v[40:43], v[40:41], off
	s_cselect_b32 s0, 16, 0
	v_lshl_add_u64 v[176:177], s[6:7], 0, v[52:53]
	v_cmp_gt_u32_e64 s[4:5], 32, v46
	s_waitcnt lgkmcnt(0)
	v_and_b32_e32 v61, 0xffff0000, v4
	v_lshlrev_b32_e32 v60, 16, v4
	v_pk_mul_f32 v[60:61], v[44:45], v[60:61] op_sel_hi:[0,1]
	s_waitcnt vmcnt(7)
	v_pk_mul_f32 v[16:17], v[16:17], v[60:61]
	v_and_b32_e32 v61, 0xffff0000, v8
	v_lshlrev_b32_e32 v60, 16, v8
	v_pk_mul_f32 v[60:61], v[44:45], v[60:61] op_sel_hi:[0,1]
	v_cvt_pk_bf16_f32 v140, v16, v17
	s_waitcnt vmcnt(5)
	v_pk_mul_f32 v[20:21], v[20:21], v[60:61]
	v_and_b32_e32 v61, 0xffff0000, v5
	v_lshlrev_b32_e32 v60, 16, v5
	v_pk_mul_f32 v[4:5], v[44:45], v[60:61] op_sel_hi:[0,1]
	v_pk_mul_f32 v[4:5], v[4:5], v[18:19]
	v_and_b32_e32 v19, 0xffff0000, v9
	v_lshlrev_b32_e32 v18, 16, v9
	v_pk_mul_f32 v[8:9], v[44:45], v[18:19] op_sel_hi:[0,1]
	v_and_b32_e32 v19, 0xffff0000, v6
	v_lshlrev_b32_e32 v18, 16, v6
	v_pk_mul_f32 v[18:19], v[44:45], v[18:19] op_sel_hi:[0,1]
	v_pk_mul_f32 v[12:13], v[18:19], v[12:13]
	v_and_b32_e32 v19, 0xffff0000, v10
	v_lshlrev_b32_e32 v18, 16, v10
	v_pk_mul_f32 v[18:19], v[44:45], v[18:19] op_sel_hi:[0,1]
	v_pk_mul_f32 v[0:1], v[18:19], v[0:1]
	v_and_b32_e32 v19, 0xffff0000, v7
	v_lshlrev_b32_e32 v18, 16, v7
	v_pk_mul_f32 v[6:7], v[44:45], v[18:19] op_sel_hi:[0,1]
	v_pk_mul_f32 v[6:7], v[6:7], v[14:15]
	v_and_b32_e32 v15, 0xffff0000, v11
	v_lshlrev_b32_e32 v14, 16, v11
	v_pk_mul_f32 v[10:11], v[44:45], v[14:15] op_sel_hi:[0,1]
	v_cvt_pk_bf16_f32 v138, v0, v1
	v_and_b32_e32 v0, 0xfffff0, v48
	v_lshlrev_b32_e32 v1, 1, v48
	v_pk_mul_f32 v[2:3], v[10:11], v[2:3]
	v_and_or_b32 v0, v1, 8, v0
	v_cvt_pk_bf16_f32 v139, v2, v3
	v_lshrrev_b32_e32 v1, 1, v48
	v_lshrrev_b32_e32 v0, 1, v0
	v_bfe_u32 v2, v47, 5, 2
	v_and_b32_e32 v3, 3, v48
	v_or_b32_e32 v0, v0, v2
	v_and_or_b32 v1, v1, 4, v3
	v_lshlrev_b32_e32 v3, 4, v45
	v_cvt_pk_bf16_f32 v141, v4, v5
	v_lshlrev_b32_e32 v0, 9, v0
	v_lshlrev_b32_e32 v1, 6, v1
	v_and_b32_e32 v4, 48, v3
	v_or3_b32 v196, v0, v1, v4
	v_and_b32_e32 v0, 0xfffff0, v50
	v_lshlrev_b32_e32 v5, 1, v50
	v_and_or_b32 v0, v5, 8, v0
	v_lshrrev_b32_e32 v0, 1, v0
	v_or_b32_e32 v0, v0, v2
	v_lshlrev_b32_e32 v0, 9, v0
	v_or3_b32 v198, v0, v1, v4
	v_add_u32_e32 v0, 16, v196
	s_waitcnt vmcnt(4)
	ds_write_b128 v0, v[24:27]
	v_add_u32_e32 v0, 16, v198
	s_waitcnt vmcnt(3)
	ds_write_b128 v0, v[28:31]
	v_mul_lo_u32 v0, v62, s30
	v_bitop3_b32 v1, v62, v63, 7 bitop3:0x6c
	v_lshl_add_u32 v200, v1, 4, v0
	v_add_u32_e32 v0, 16, v200
	s_waitcnt vmcnt(2)
	ds_write_b128 v0, v[32:35] offset:32768
	v_mul_lo_u32 v0, v64, s30
	v_bitop3_b32 v1, v64, v65, 7 bitop3:0x6c
	v_lshl_add_u32 v201, v1, 4, v0
	v_add_u32_e32 v0, 16, v201
	s_waitcnt vmcnt(1)
	ds_write_b128 v0, v[36:39] offset:32768
	v_mul_lo_u32 v0, v66, s30
	v_bitop3_b32 v1, v66, v67, 7 bitop3:0x6c
	v_lshl_add_u32 v205, v1, 4, v0
	v_add_u32_e32 v0, 16, v205
	v_and_b32_e32 v1, 0x118, v47
	s_waitcnt vmcnt(0)
	ds_write_b128 v0, v[40:43] offset:32768
	v_lshlrev_b32_e32 v0, 1, v45
	v_and_b32_e32 v2, 0xc0, v3
	v_and_or_b32 v0, v0, 32, v1
	v_add3_u32 v185, v2, s0, v0
	s_add_u32 s0, s68, 0xc006000
	s_addc_u32 s1, s23, 0
	v_mov_b64_e32 v[0:1], s[0:1]
	v_and_b32_e32 v4, 0x70, v3
	v_bitop3_b32 v206, v166, v3, s36 bitop3:0x78
	v_mad_i64_i32 v[2:3], s[0:1], v66, s30, v[0:1]
	v_lshl_add_u64 v[170:171], v[2:3], 0, v[58:59]
	v_mad_i64_i32 v[2:3], s[0:1], v64, s30, v[0:1]
	v_mad_i64_i32 v[0:1], s[0:1], v62, s30, v[0:1]
	v_pk_mul_f32 v[8:9], v[8:9], v[22:23]
	v_lshl_add_u64 v[174:175], v[0:1], 0, v[54:55]
	v_and_b32_e32 v0, 15, v45
	v_mov_b32_e32 v14, v165
	v_mov_b32_e32 v15, v165
	v_cvt_pk_bf16_f32 v142, v12, v13
	v_cvt_pk_bf16_f32 v143, v6, v7
	v_cvt_pk_bf16_f32 v136, v20, v21
	v_cvt_pk_bf16_f32 v137, v8, v9
	v_bitop3_b32 v203, v166, v4, 32 bitop3:0x36
	v_bitop3_b32 v202, v166, v4, 64 bitop3:0x36
	v_bitop3_b32 v199, v166, v4, s37 bitop3:0x36
	v_bitop3_b32 v197, v166, v4, s38 bitop3:0x36
	v_bitop3_b32 v195, v166, v4, s39 bitop3:0x36
	v_bitop3_b32 v194, v166, v4, s35 bitop3:0x36
	v_bitop3_b32 v193, v166, v4, s40 bitop3:0x36
	v_bitop3_b32 v192, v166, v4, s41 bitop3:0x36
	v_bitop3_b32 v191, v166, v4, s42 bitop3:0x36
	v_bitop3_b32 v190, v166, v4, s43 bitop3:0x36
	v_bitop3_b32 v189, v166, v4, s44 bitop3:0x36
	v_lshl_add_u64 v[172:173], v[2:3], 0, v[56:57]
	v_lshl_or_b32 v176, v0, 4, v176
	v_mov_b32_e32 v0, v165
	v_mov_b32_e32 v1, v165
	v_mov_b32_e32 v2, v165
	v_mov_b32_e32 v3, v165
	v_mov_b32_e32 v4, v165
	v_mov_b32_e32 v5, v165
	v_mov_b32_e32 v6, v165
	v_mov_b32_e32 v7, v165
	v_mov_b32_e32 v8, v165
	v_mov_b32_e32 v9, v165
	v_mov_b32_e32 v10, v165
	v_mov_b32_e32 v11, v165
	v_mov_b32_e32 v12, v165
	v_mov_b32_e32 v13, v165
	v_mov_b64_e32 v[30:31], v[14:15]
	v_mov_b64_e32 v[46:47], v[14:15]
	v_mov_b64_e32 v[62:63], v[14:15]
	v_mov_b64_e32 v[28:29], v[12:13]
	v_mov_b64_e32 v[26:27], v[10:11]
	v_mov_b64_e32 v[24:25], v[8:9]
	v_mov_b64_e32 v[22:23], v[6:7]
	v_mov_b64_e32 v[20:21], v[4:5]
	v_mov_b64_e32 v[18:19], v[2:3]
	v_mov_b64_e32 v[16:17], v[0:1]
	v_mov_b64_e32 v[44:45], v[12:13]
	v_mov_b64_e32 v[42:43], v[10:11]
	v_mov_b64_e32 v[40:41], v[8:9]
	v_mov_b64_e32 v[38:39], v[6:7]
	v_mov_b64_e32 v[36:37], v[4:5]
	v_mov_b64_e32 v[34:35], v[2:3]
	v_mov_b64_e32 v[32:33], v[0:1]
	v_mov_b64_e32 v[60:61], v[12:13]
	v_mov_b64_e32 v[58:59], v[10:11]
	v_mov_b64_e32 v[56:57], v[8:9]
	v_mov_b64_e32 v[54:55], v[6:7]
	v_mov_b64_e32 v[52:53], v[4:5]
	v_mov_b64_e32 v[50:51], v[2:3]
	v_mov_b64_e32 v[48:49], v[0:1]

.LBB0_1160:
	s_and_b64 vcc, exec, s[6:7]
	s_cbranch_vccz .LBB0_1144
	s_ashr_i32 s0, s67, 6
	s_lshl_b32 s4, s67, 8
	s_lshl_b32 s1, s0, 10
	s_and_b32 s23, s4, 0x300
	s_bfe_u32 s13, s67, 0x40002
	s_or_b32 s1, s1, s23
	s_lshl_b32 s0, s0, 4
	s_add_i32 s20, s1, 0x2000
	s_or_b32 s22, s0, s13
	s_ashr_i32 s21, s20, 31
	s_mul_i32 s1, s22, 0x500
	s_mul_hi_i32 s0, s22, 0x500
	s_add_u32 s6, s1, 0x20000
	s_addc_u32 s7, s0, 0
	s_mul_i32 s1, s20, 0x1800
	s_mul_hi_i32 s0, s20, 0x1800
	s_add_u32 s1, s76, s1
	s_addc_u32 s4, s77, s0
	s_mul_i32 s0, s13, 0x180
	s_add_u32 s0, s1, s0
	s_waitcnt vmcnt(0)
	v_mov_b32_e32 v59, v204
	s_addc_u32 s1, s4, 0
	v_mov_b64_e32 v[0:1], s[0:1]
	v_ashrrev_i32_e32 v4, 1, v59
	v_bfe_u32 v183, v59, 5, 1
	v_bfi_b32 v2, s31, v4, v59
	v_mad_i64_i32 v[0:1], s[0:1], v2, s29, v[0:1]
	v_lshlrev_b32_e32 v166, 4, v183
	v_mov_b32_e32 v167, v165
	v_lshl_add_u64 v[56:57], v[0:1], 0, v[166:167]
	s_waitcnt lgkmcnt(0)
	s_barrier
	global_load_dwordx4 v[6:9], v[56:57], off
	global_load_dwordx4 v[10:13], v[56:57], off offset:32
	global_load_dwordx4 v[14:17], v[56:57], off offset:64
	global_load_dwordx4 v[18:21], v[56:57], off offset:96
	global_load_dwordx4 v[22:25], v[56:57], off offset:128
	global_load_dwordx4 v[26:29], v[56:57], off offset:160
	global_load_dwordx4 v[30:33], v[56:57], off offset:192
	global_load_dwordx4 v[34:37], v[56:57], off offset:224
	global_load_dwordx4 v[38:41], v[56:57], off offset:256
	global_load_dwordx4 v[0:3], v[56:57], off offset:288
	v_cmp_lt_i32_e32 vcc, v180, v181
	v_and_b32_e32 v164, 31, v59
	v_and_b32_e32 v168, 0xffffffe0, v4
	s_mul_hi_u32 s0, s6, 0x180
	s_mul_i32 s4, s7, 0x180
	s_mul_i32 s1, s6, 0x180
	s_add_i32 s0, s0, s4
	s_add_u32 s4, s2, s1
	s_addc_u32 s5, s3, s0
	s_lshl_b64 s[0:1], s[6:7], 8
	s_add_u32 s6, s24, s0
	s_addc_u32 s7, s25, s1
	s_cmp_lg_u32 16, -1
	s_mov_b32 s14, 0
	v_mul_u32_u24_e32 v188, 0x180, v164
	v_mov_b32_e32 v207, 0
	v_mov_b32_e32 v186, 0xf149f2ca
	s_waitcnt vmcnt(9)
	v_lshlrev_b32_e32 v5, 16, v6
	v_and_b32_e32 v6, 0xffff0000, v6
	v_mul_f32_e32 v65, v6, v6
	v_lshlrev_b32_e32 v42, 16, v7
	v_fmac_f32_e32 v65, v5, v5
	v_and_b32_e32 v7, 0xffff0000, v7
	v_fmac_f32_e32 v65, v42, v42
	v_lshlrev_b32_e32 v43, 16, v8
	v_fmac_f32_e32 v65, v7, v7
	v_and_b32_e32 v8, 0xffff0000, v8
	v_fmac_f32_e32 v65, v43, v43
	v_lshlrev_b32_e32 v44, 16, v9
	v_fmac_f32_e32 v65, v8, v8
	v_and_b32_e32 v9, 0xffff0000, v9
	v_fmac_f32_e32 v65, v44, v44
	s_waitcnt vmcnt(8)
	v_lshlrev_b32_e32 v45, 16, v10
	v_fmac_f32_e32 v65, v9, v9
	v_and_b32_e32 v10, 0xffff0000, v10
	v_fmac_f32_e32 v65, v45, v45
	v_lshlrev_b32_e32 v46, 16, v11
	v_fmac_f32_e32 v65, v10, v10
	v_and_b32_e32 v11, 0xffff0000, v11
	v_fmac_f32_e32 v65, v46, v46
	v_lshlrev_b32_e32 v47, 16, v12
	v_fmac_f32_e32 v65, v11, v11
	v_and_b32_e32 v12, 0xffff0000, v12
	v_fmac_f32_e32 v65, v47, v47
	v_lshlrev_b32_e32 v48, 16, v13
	v_fmac_f32_e32 v65, v12, v12
	v_and_b32_e32 v13, 0xffff0000, v13
	v_fmac_f32_e32 v65, v48, v48
	s_waitcnt vmcnt(7)
	v_lshlrev_b32_e32 v49, 16, v14
	v_fmac_f32_e32 v65, v13, v13
	v_and_b32_e32 v14, 0xffff0000, v14
	v_fmac_f32_e32 v65, v49, v49
	v_lshlrev_b32_e32 v50, 16, v15
	v_fmac_f32_e32 v65, v14, v14
	v_and_b32_e32 v15, 0xffff0000, v15
	v_fmac_f32_e32 v65, v50, v50
	v_lshlrev_b32_e32 v51, 16, v16
	v_fmac_f32_e32 v65, v15, v15
	v_and_b32_e32 v16, 0xffff0000, v16
	v_fmac_f32_e32 v65, v51, v51
	v_lshlrev_b32_e32 v52, 16, v17
	v_fmac_f32_e32 v65, v16, v16
	v_and_b32_e32 v17, 0xffff0000, v17
	v_fmac_f32_e32 v65, v52, v52
	s_waitcnt vmcnt(6)
	v_lshlrev_b32_e32 v53, 16, v18
	v_fmac_f32_e32 v65, v17, v17
	v_and_b32_e32 v18, 0xffff0000, v18
	v_fmac_f32_e32 v65, v53, v53
	v_lshlrev_b32_e32 v54, 16, v19
	v_fmac_f32_e32 v65, v18, v18
	v_and_b32_e32 v19, 0xffff0000, v19
	v_fmac_f32_e32 v65, v54, v54
	v_lshlrev_b32_e32 v55, 16, v20
	v_fmac_f32_e32 v65, v19, v19
	v_and_b32_e32 v20, 0xffff0000, v20
	v_fmac_f32_e32 v65, v55, v55
	v_lshlrev_b32_e32 v58, 16, v21
	v_fmac_f32_e32 v65, v20, v20
	v_and_b32_e32 v21, 0xffff0000, v21
	v_fmac_f32_e32 v65, v58, v58
	s_waitcnt vmcnt(5)
	v_lshlrev_b32_e32 v60, 16, v22
	v_fmac_f32_e32 v65, v21, v21
	v_and_b32_e32 v22, 0xffff0000, v22
	v_fmac_f32_e32 v65, v60, v60
	v_lshlrev_b32_e32 v61, 16, v23
	v_fmac_f32_e32 v65, v22, v22
	v_and_b32_e32 v23, 0xffff0000, v23
	v_fmac_f32_e32 v65, v61, v61
	v_lshlrev_b32_e32 v62, 16, v24
	v_fmac_f32_e32 v65, v23, v23
	v_and_b32_e32 v24, 0xffff0000, v24
	v_fmac_f32_e32 v65, v62, v62
	v_lshlrev_b32_e32 v63, 16, v25
	v_fmac_f32_e32 v65, v24, v24
	global_load_dwordx4 v[6:9], v[56:57], off offset:320
	v_and_b32_e32 v25, 0xffff0000, v25
	v_fmac_f32_e32 v65, v63, v63
	s_waitcnt vmcnt(5)
	v_lshlrev_b32_e32 v64, 16, v26
	v_fmac_f32_e32 v65, v25, v25
	v_fmac_f32_e32 v65, v64, v64
	v_and_b32_e32 v5, 0xffff0000, v26
	v_fmac_f32_e32 v65, v5, v5
	v_lshlrev_b32_e32 v5, 16, v27
	v_fmac_f32_e32 v65, v5, v5
	v_and_b32_e32 v5, 0xffff0000, v27
	v_fmac_f32_e32 v65, v5, v5
	v_lshlrev_b32_e32 v5, 16, v28
	v_fmac_f32_e32 v65, v5, v5
	v_and_b32_e32 v5, 0xffff0000, v28
	v_fmac_f32_e32 v65, v5, v5
	v_lshlrev_b32_e32 v5, 16, v29
	v_fmac_f32_e32 v65, v5, v5
	v_and_b32_e32 v5, 0xffff0000, v29
	global_load_dwordx4 v[26:29], v[56:57], off offset:352
	v_fmac_f32_e32 v65, v5, v5
	s_waitcnt vmcnt(5)
	v_lshlrev_b32_e32 v5, 16, v30
	v_fmac_f32_e32 v65, v5, v5
	v_and_b32_e32 v5, 0xffff0000, v30
	v_fmac_f32_e32 v65, v5, v5
	v_lshlrev_b32_e32 v5, 16, v31
	v_fmac_f32_e32 v65, v5, v5
	v_and_b32_e32 v5, 0xffff0000, v31
	v_fmac_f32_e32 v65, v5, v5
	v_lshlrev_b32_e32 v5, 16, v32
	v_fmac_f32_e32 v65, v5, v5
	v_and_b32_e32 v5, 0xffff0000, v32
	v_fmac_f32_e32 v65, v5, v5
	v_lshlrev_b32_e32 v5, 16, v33
	v_fmac_f32_e32 v65, v5, v5
	v_and_b32_e32 v5, 0xffff0000, v33
	v_fmac_f32_e32 v65, v5, v5
	s_waitcnt vmcnt(4)
	v_lshlrev_b32_e32 v5, 16, v34
	v_fmac_f32_e32 v65, v5, v5
	v_and_b32_e32 v5, 0xffff0000, v34
	v_fmac_f32_e32 v65, v5, v5
	v_lshlrev_b32_e32 v5, 16, v35
	v_fmac_f32_e32 v65, v5, v5
	v_and_b32_e32 v5, 0xffff0000, v35
	v_fmac_f32_e32 v65, v5, v5
	v_lshlrev_b32_e32 v5, 16, v36
	v_fmac_f32_e32 v65, v5, v5
	v_and_b32_e32 v5, 0xffff0000, v36
	v_fmac_f32_e32 v65, v5, v5
	v_lshlrev_b32_e32 v5, 16, v37
	v_fmac_f32_e32 v65, v5, v5
	v_and_b32_e32 v5, 0xffff0000, v37
	v_fmac_f32_e32 v65, v5, v5
	s_waitcnt vmcnt(3)
	v_lshlrev_b32_e32 v5, 16, v38
	v_fmac_f32_e32 v65, v5, v5
	v_and_b32_e32 v5, 0xffff0000, v38
	v_fmac_f32_e32 v65, v5, v5
	v_lshlrev_b32_e32 v5, 16, v39
	v_fmac_f32_e32 v65, v5, v5
	v_and_b32_e32 v5, 0xffff0000, v39
	v_fmac_f32_e32 v65, v5, v5
	v_lshlrev_b32_e32 v5, 16, v40
	global_load_dwordx4 v[20:23], v[56:57], off
	global_load_dwordx4 v[12:15], v[56:57], off offset:32
	s_waitcnt vmcnt(0)
	v_and_b32_e32 v61, 32, v59
	v_fmac_f32_e32 v65, v5, v5
	v_and_b32_e32 v5, 0xffff0000, v40
	global_load_dwordx4 v[32:35], v61, s[10:11] offset:16
	global_load_dwordx4 v[48:51], v61, s[10:11]
	v_fmac_f32_e32 v65, v5, v5
	v_lshlrev_b32_e32 v5, 16, v41
	v_fmac_f32_e32 v65, v5, v5
	v_and_b32_e32 v5, 0xffff0000, v41
	global_load_dwordx4 v[40:43], v61, s[10:11] offset:80
	global_load_dwordx4 v[52:55], v61, s[10:11] offset:64
	v_fmac_f32_e32 v65, v5, v5
	v_lshlrev_b32_e32 v5, 16, v0
	v_fmac_f32_e32 v65, v5, v5
	v_and_b32_e32 v0, 0xffff0000, v0
	v_fmac_f32_e32 v65, v0, v0
	v_lshlrev_b32_e32 v0, 16, v1
	v_fmac_f32_e32 v65, v0, v0
	v_and_b32_e32 v0, 0xffff0000, v1
	v_fmac_f32_e32 v65, v0, v0
	v_lshlrev_b32_e32 v0, 16, v2
	v_fmac_f32_e32 v65, v0, v0
	v_and_b32_e32 v0, 0xffff0000, v2
	v_fmac_f32_e32 v65, v0, v0
	v_lshlrev_b32_e32 v0, 16, v3
	v_fmac_f32_e32 v65, v0, v0
	v_and_b32_e32 v0, 0xffff0000, v3
	v_fmac_f32_e32 v65, v0, v0
	v_lshlrev_b32_e32 v0, 16, v6
	v_fmac_f32_e32 v65, v0, v0
	v_and_b32_e32 v0, 0xffff0000, v6
	v_fmac_f32_e32 v65, v0, v0
	v_lshlrev_b32_e32 v0, 16, v7
	v_fmac_f32_e32 v65, v0, v0
	v_and_b32_e32 v0, 0xffff0000, v7
	v_fmac_f32_e32 v65, v0, v0
	v_lshlrev_b32_e32 v0, 16, v8
	v_fmac_f32_e32 v65, v0, v0
	v_and_b32_e32 v0, 0xffff0000, v8
	v_fmac_f32_e32 v65, v0, v0
	v_and_b32_e32 v1, 0xffff0000, v9
	v_lshlrev_b32_e32 v0, 16, v9
	v_pk_mul_f32 v[0:1], v[0:1], v[0:1]
	v_lshlrev_b32_e32 v62, 3, v183
	v_add_f32_e32 v0, v0, v65
	v_add_f32_e32 v2, v1, v0
	v_and_b32_e32 v1, 0xffff0000, v26
	v_lshlrev_b32_e32 v0, 16, v26
	v_pk_mul_f32 v[0:1], v[0:1], v[0:1]
	v_and_b32_e32 v60, 63, v59
	v_add_f32_e32 v0, v0, v2
	v_add_f32_e32 v2, v1, v0
	v_and_b32_e32 v1, 0xffff0000, v27
	v_lshlrev_b32_e32 v0, 16, v27
	v_pk_mul_f32 v[0:1], v[0:1], v[0:1]
	global_load_dwordx4 v[24:27], v[56:57], off offset:64
	global_load_dwordx4 v[16:19], v[56:57], off offset:96
	s_waitcnt vmcnt(0)
	global_load_dwordx4 v[36:39], v61, s[10:11] offset:144
	global_load_dwordx4 v[64:67], v61, s[10:11] offset:128
	v_add_f32_e32 v0, v0, v2
	v_add_f32_e32 v2, v1, v0
	v_and_b32_e32 v1, 0xffff0000, v28
	v_lshlrev_b32_e32 v0, 16, v28
	v_pk_mul_f32 v[0:1], v[0:1], v[0:1]
	global_load_dwordx4 v[44:47], v61, s[10:11] offset:208
	global_load_dwordx4 v[68:71], v61, s[10:11] offset:192
	v_add_f32_e32 v0, v0, v2
	v_add_f32_e32 v2, v1, v0
	v_and_b32_e32 v1, 0xffff0000, v29
	v_lshlrev_b32_e32 v0, 16, v29
	v_pk_mul_f32 v[0:1], v[0:1], v[0:1]
	s_waitcnt lgkmcnt(0)
	v_and_b32_e32 v79, 0xffff0000, v13
	v_add_f32_e32 v0, v0, v2
	v_add_f32_e32 v0, v1, v0
	v_cndmask_b32_e32 v1, v179, v180, vcc
	v_lshlrev_b32_e32 v1, 2, v1
	ds_bpermute_b32 v1, v1, v0
	v_and_b32_e32 v2, 0x3fffffc0, v59
	v_lshl_add_u32 v167, v2, 2, s66
	v_lshlrev_b32_e32 v78, 16, v13
	v_lshl_add_u32 v184, v164, 2, v167
	s_waitcnt lgkmcnt(0)
	v_add_f32_e32 v0, v0, v1
	v_fmamk_f32 v0, v0, 0x3baaaaab, v178
	v_mul_f32_e32 v1, 0x4b800000, v0
	v_cmp_gt_f32_e32 vcc, s33, v0
	v_add_u32_e32 v169, v167, v166
	s_nop 0
	v_cndmask_b32_e32 v0, v0, v1, vcc
	v_rsq_f32_e32 v0, v0
	s_nop 0
	v_mul_f32_e32 v1, 0x45800000, v0
	v_cndmask_b32_e32 v58, v0, v1, vcc
	v_or_b32_e32 v0, s23, v164
	v_add_u32_e32 v63, v0, v168
	v_and_b32_e32 v1, 0xffff0000, v20
	v_lshlrev_b32_e32 v0, 16, v20
	v_pk_mul_f32 v[0:1], v[58:59], v[0:1] op_sel_hi:[0,1]
	v_pk_mul_f32 v[76:77], v[48:49], v[0:1]
	v_and_b32_e32 v1, 0xffff0000, v12
	v_lshlrev_b32_e32 v0, 16, v12
	v_pk_mul_f32 v[0:1], v[58:59], v[0:1] op_sel_hi:[0,1]
	v_pk_mul_f32 v[52:53], v[52:53], v[0:1]
	v_and_b32_e32 v1, 0xffff0000, v21
	v_lshlrev_b32_e32 v0, 16, v21
	v_pk_mul_f32 v[0:1], v[58:59], v[0:1] op_sel_hi:[0,1]
	v_pk_mul_f32 v[20:21], v[50:51], v[0:1]
	global_load_dwordx4 v[4:7], v[56:57], off offset:128
	global_load_dwordx4 v[0:3], v[56:57], off offset:160
	s_waitcnt vmcnt(0)
	global_load_dwordx4 v[8:11], v61, s[10:11] offset:272
	global_load_dwordx4 v[48:51], v61, s[10:11] offset:256
	global_load_dwordx4 v[28:31], v61, s[10:11] offset:336
	global_load_dwordx4 v[72:75], v61, s[10:11] offset:320
	v_pk_mul_f32 v[12:13], v[58:59], v[78:79] op_sel_hi:[0,1]
	v_pk_mul_f32 v[12:13], v[54:55], v[12:13]
	v_and_b32_e32 v55, 0xffff0000, v22
	v_lshlrev_b32_e32 v54, 16, v22
	v_pk_mul_f32 v[54:55], v[58:59], v[54:55] op_sel_hi:[0,1]
	v_pk_mul_f32 v[32:33], v[32:33], v[54:55]
	v_and_b32_e32 v55, 0xffff0000, v14
	v_lshlrev_b32_e32 v54, 16, v14
	v_pk_mul_f32 v[54:55], v[58:59], v[54:55] op_sel_hi:[0,1]
	v_cvt_pk_bf16_f32 v97, v12, v13
	v_pk_mul_f32 v[40:41], v[40:41], v[54:55]
	v_and_b32_e32 v55, 0xffff0000, v23
	v_and_b32_e32 v13, 0xffff0000, v24
	v_lshlrev_b32_e32 v12, 16, v24
	v_lshlrev_b32_e32 v54, 16, v23
	v_pk_mul_f32 v[12:13], v[58:59], v[12:13] op_sel_hi:[0,1]
	v_pk_mul_f32 v[22:23], v[58:59], v[54:55] op_sel_hi:[0,1]
	v_cvt_pk_bf16_f32 v101, v20, v21
	v_pk_mul_f32 v[20:21], v[64:65], v[12:13]
	v_and_b32_e32 v13, 0xffff0000, v16
	v_lshlrev_b32_e32 v12, 16, v16
	v_pk_mul_f32 v[22:23], v[34:35], v[22:23]
	v_pk_mul_f32 v[12:13], v[58:59], v[12:13] op_sel_hi:[0,1]
	v_cvt_pk_bf16_f32 v103, v22, v23
	v_pk_mul_f32 v[22:23], v[68:69], v[12:13]
	v_and_b32_e32 v13, 0xffff0000, v25
	v_lshlrev_b32_e32 v12, 16, v25
	v_pk_mul_f32 v[12:13], v[58:59], v[12:13] op_sel_hi:[0,1]
	v_pk_mul_f32 v[24:25], v[66:67], v[12:13]
	v_and_b32_e32 v13, 0xffff0000, v17
	v_lshlrev_b32_e32 v12, 16, v17
	v_pk_mul_f32 v[12:13], v[58:59], v[12:13] op_sel_hi:[0,1]
	v_pk_mul_f32 v[16:17], v[70:71], v[12:13]
	v_and_b32_e32 v13, 0xffff0000, v26
	v_lshlrev_b32_e32 v12, 16, v26
	v_pk_mul_f32 v[12:13], v[58:59], v[12:13] op_sel_hi:[0,1]
	v_cvt_pk_bf16_f32 v105, v16, v17
	v_and_b32_e32 v35, 0xffff0000, v15
	v_lshlrev_b32_e32 v34, 16, v15
	v_cvt_pk_bf16_f32 v102, v32, v33
	v_pk_mul_f32 v[32:33], v[36:37], v[12:13]
	v_and_b32_e32 v37, 0xffff0000, v27
	v_lshlrev_b32_e32 v36, 16, v27
	v_pk_mul_f32 v[14:15], v[58:59], v[34:35] op_sel_hi:[0,1]
	v_pk_mul_f32 v[26:27], v[58:59], v[36:37] op_sel_hi:[0,1]
	v_and_b32_e32 v37, 0xffff0000, v19
	v_lshlrev_b32_e32 v36, 16, v19
	v_pk_mul_f32 v[14:15], v[42:43], v[14:15]
	v_and_b32_e32 v35, 0xffff0000, v18
	v_lshlrev_b32_e32 v34, 16, v18
	v_pk_mul_f32 v[18:19], v[58:59], v[36:37] op_sel_hi:[0,1]
	v_cvt_pk_bf16_f32 v100, v76, v77
	v_cvt_pk_bf16_f32 v99, v14, v15
	global_load_dwordx4 v[12:15], v[56:57], off offset:192
	global_load_dwordx4 v[64:67], v[56:57], off offset:224
	s_waitcnt vmcnt(0)
	global_load_dwordx4 v[68:71], v61, s[10:11] offset:400
	global_load_dwordx4 v[76:79], v61, s[10:11] offset:384
	global_load_dwordx4 v[80:83], v61, s[10:11] offset:464
	global_load_dwordx4 v[84:87], v61, s[10:11] offset:448
	v_pk_mul_f32 v[18:19], v[46:47], v[18:19]
	v_cvt_pk_bf16_f32 v109, v24, v25
	v_pk_mul_f32 v[34:35], v[58:59], v[34:35] op_sel_hi:[0,1]
	v_cvt_pk_bf16_f32 v108, v20, v21
	v_cvt_pk_bf16_f32 v104, v22, v23
	v_cvt_pk_bf16_f32 v107, v18, v19
	v_pk_mul_f32 v[34:35], v[44:45], v[34:35]
	v_pk_mul_f32 v[26:27], v[38:39], v[26:27]
	v_cvt_pk_bf16_f32 v96, v52, v53
	v_cvt_pk_bf16_f32 v98, v40, v41
	v_cvt_pk_bf16_f32 v110, v32, v33
	v_cvt_pk_bf16_f32 v111, v26, v27
	v_cvt_pk_bf16_f32 v106, v34, v35
	s_waitcnt lgkmcnt(0)
	v_and_b32_e32 v17, 0xffff0000, v4
	v_lshlrev_b32_e32 v16, 16, v4
	v_pk_mul_f32 v[16:17], v[58:59], v[16:17] op_sel_hi:[0,1]
	v_pk_mul_f32 v[92:93], v[48:49], v[16:17]
	v_and_b32_e32 v17, 0xffff0000, v0
	v_lshlrev_b32_e32 v16, 16, v0
	v_ashrrev_i32_e32 v0, 2, v63
	v_pk_mul_f32 v[16:17], v[58:59], v[16:17] op_sel_hi:[0,1]
	v_and_or_b32 v0, v0, s49, v62
	v_pk_mul_f32 v[72:73], v[72:73], v[16:17]
	v_and_b32_e32 v17, 0xffff0000, v5
	v_lshlrev_b32_e32 v16, 16, v5
	v_lshlrev_b32_e32 v24, 1, v0
	v_pk_mul_f32 v[4:5], v[58:59], v[16:17] op_sel_hi:[0,1]
	global_load_dwordx4 v[16:19], v[56:57], off offset:256
	global_load_dwordx4 v[20:23], v[56:57], off offset:288
	s_waitcnt vmcnt(0)
	v_ashrrev_i32_e32 v25, 31, v24
	v_lshl_add_u64 v[88:89], v[24:25], 2, s[8:9]
	v_and_b32_e32 v91, 0xffff0000, v1
	v_lshlrev_b32_e32 v90, 16, v1
	v_pk_mul_f32 v[4:5], v[50:51], v[4:5]
	global_load_dwordx4 v[32:35], v61, s[10:11] offset:528
	global_load_dwordx4 v[48:51], v61, s[10:11] offset:512
	global_load_dwordx4 v[40:43], v61, s[10:11] offset:592
	global_load_dwordx4 v[24:27], v61, s[10:11] offset:576
	global_load_dwordx4 v[52:55], v[88:89], off offset:16
	global_load_dwordx4 v[36:39], v[88:89], off offset:48
	global_load_dwordx4 v[44:47], v[88:89], off offset:32
	v_pk_mul_f32 v[0:1], v[58:59], v[90:91] op_sel_hi:[0,1]
	global_load_dwordx4 v[88:91], v[88:89], off
	v_pk_mul_f32 v[0:1], v[74:75], v[0:1]
	v_and_b32_e32 v75, 0xffff0000, v6
	v_lshlrev_b32_e32 v74, 16, v6
	v_pk_mul_f32 v[74:75], v[58:59], v[74:75] op_sel_hi:[0,1]
	v_pk_mul_f32 v[8:9], v[8:9], v[74:75]
	v_and_b32_e32 v75, 0xffff0000, v2
	v_lshlrev_b32_e32 v74, 16, v2
	v_pk_mul_f32 v[74:75], v[58:59], v[74:75] op_sel_hi:[0,1]
	v_pk_mul_f32 v[28:29], v[28:29], v[74:75]
	v_and_b32_e32 v75, 0xffff0000, v7
	v_lshlrev_b32_e32 v74, 16, v7
	v_pk_mul_f32 v[6:7], v[58:59], v[74:75] op_sel_hi:[0,1]
	v_pk_mul_f32 v[6:7], v[10:11], v[6:7]
	v_and_b32_e32 v11, 0xffff0000, v3
	v_lshlrev_b32_e32 v10, 16, v3
	v_pk_mul_f32 v[2:3], v[58:59], v[10:11] op_sel_hi:[0,1]
	v_pk_mul_f32 v[2:3], v[30:31], v[2:3]
	v_cvt_pk_bf16_f32 v113, v0, v1
	v_cvt_pk_bf16_f32 v115, v2, v3
	v_cvt_pk_bf16_f32 v117, v4, v5
	v_cvt_pk_bf16_f32 v119, v6, v7
	v_cvt_pk_bf16_f32 v118, v8, v9
	v_cvt_pk_bf16_f32 v112, v72, v73
	v_cvt_pk_bf16_f32 v114, v28, v29
	v_cvt_pk_bf16_f32 v116, v92, v93
	v_and_b32_e32 v1, 0xffff0000, v12
	v_and_b32_e32 v3, 0xffff0000, v64
	v_lshlrev_b32_e32 v2, 16, v64
	v_lshlrev_b32_e32 v0, 16, v12
	v_pk_mul_f32 v[2:3], v[58:59], v[2:3] op_sel_hi:[0,1]
	v_pk_mul_f32 v[0:1], v[58:59], v[0:1] op_sel_hi:[0,1]
	v_pk_mul_f32 v[2:3], v[84:85], v[2:3]
	v_and_b32_e32 v5, 0xffff0000, v13
	v_lshlrev_b32_e32 v4, 16, v13
	v_pk_mul_f32 v[0:1], v[76:77], v[0:1]
	v_pk_mul_f32 v[4:5], v[58:59], v[4:5] op_sel_hi:[0,1]
	v_and_b32_e32 v7, 0xffff0000, v65
	v_lshlrev_b32_e32 v6, 16, v65
	v_cvt_pk_bf16_f32 v120, v2, v3
	v_pk_mul_f32 v[4:5], v[78:79], v[4:5]
	v_pk_mul_f32 v[6:7], v[58:59], v[6:7] op_sel_hi:[0,1]
	v_cvt_pk_bf16_f32 v124, v0, v1
	v_pk_mul_f32 v[6:7], v[86:87], v[6:7]
	v_cvt_pk_bf16_f32 v125, v4, v5
	v_and_b32_e32 v9, 0xffff0000, v14
	v_lshlrev_b32_e32 v8, 16, v14
	v_and_b32_e32 v11, 0xffff0000, v66
	v_lshlrev_b32_e32 v10, 16, v66
	v_and_b32_e32 v13, 0xffff0000, v15
	v_lshlrev_b32_e32 v12, 16, v15
	v_and_b32_e32 v15, 0xffff0000, v67
	v_lshlrev_b32_e32 v14, 16, v67
	v_cvt_pk_bf16_f32 v121, v6, v7
	v_pk_mul_f32 v[8:9], v[58:59], v[8:9] op_sel_hi:[0,1]
	v_pk_mul_f32 v[10:11], v[58:59], v[10:11] op_sel_hi:[0,1]
	v_pk_mul_f32 v[12:13], v[58:59], v[12:13] op_sel_hi:[0,1]
	v_pk_mul_f32 v[14:15], v[58:59], v[14:15] op_sel_hi:[0,1]
	v_pk_mul_f32 v[8:9], v[68:69], v[8:9]
	v_pk_mul_f32 v[10:11], v[80:81], v[10:11]
	v_pk_mul_f32 v[12:13], v[70:71], v[12:13]
	v_pk_mul_f32 v[14:15], v[82:83], v[14:15]
	v_cvt_pk_bf16_f32 v126, v8, v9
	v_cvt_pk_bf16_f32 v127, v12, v13
	s_waitcnt lgkmcnt(0)
	v_and_b32_e32 v1, 0xffff0000, v16
	v_and_b32_e32 v3, 0xffff0000, v20
	v_lshlrev_b32_e32 v2, 16, v20
	v_lshlrev_b32_e32 v0, 16, v16
	v_pk_mul_f32 v[2:3], v[58:59], v[2:3] op_sel_hi:[0,1]
	v_pk_mul_f32 v[0:1], v[58:59], v[0:1] op_sel_hi:[0,1]
	s_waitcnt vmcnt(4)
	v_pk_mul_f32 v[2:3], v[24:25], v[2:3]
	v_pk_mul_f32 v[0:1], v[48:49], v[0:1]
	v_cvt_pk_bf16_f32 v122, v10, v11
	v_cvt_pk_bf16_f32 v123, v14, v15
	s_waitcnt vmcnt(0)
	v_mov_b32_e32 v4, v88
	v_mov_b32_e32 v5, v90
	v_mov_b32_e32 v90, v89
	v_pk_mul_f32 v[6:7], v[90:91], v[2:3]
	v_pk_mul_f32 v[2:3], v[4:5], v[2:3]
	v_pk_fma_f32 v[82:83], v[4:5], v[0:1], v[6:7] neg_lo:[0,0,1] neg_hi:[0,0,1]
	v_pk_fma_f32 v[84:85], v[90:91], v[0:1], v[2:3]
	v_lshlrev_b32_e32 v3, 4, v63
	v_and_b32_e32 v1, 0xffff0000, v17
	v_lshlrev_b32_e32 v0, 16, v21
	v_and_or_b32 v3, v3, s50, v62
	v_pk_mul_f32 v[0:1], v[58:59], v[0:1] op_sel_hi:[0,1]
	v_mov_b32_e32 v2, v26
	global_load_dwordx4 v[4:7], v[56:57], off offset:320
	global_load_dwordx4 v[8:11], v[56:57], off offset:352
	s_waitcnt vmcnt(0)
	v_lshlrev_b32_e32 v12, 3, v3
	v_mov_b32_e32 v3, v51
	global_load_dwordx4 v[62:65], v12, s[8:9] offset:16
	global_load_dwordx4 v[66:69], v12, s[8:9]
	v_pk_mul_f32 v[56:57], v[2:3], v[0:1]
	global_load_dwordx4 v[0:3], v12, s[8:9] offset:48
	s_nop 0
	global_load_dwordx4 v[12:15], v12, s[8:9] offset:32
	v_mov_b32_e32 v51, v27
	global_load_dwordx4 v[24:27], v61, s[10:11] offset:720
	global_load_dwordx4 v[70:73], v61, s[10:11] offset:704
	global_load_dwordx4 v[28:31], v61, s[10:11] offset:656
	global_load_dwordx4 v[74:77], v61, s[10:11] offset:640
	v_and_b32_e32 v21, 0xffff0000, v21
	v_lshlrev_b32_e32 v20, 16, v17
	v_pk_mul_f32 v[16:17], v[58:59], v[20:21] op_sel_hi:[0,1]
	v_pk_mul_f32 v[16:17], v[50:51], v[16:17]
	v_mov_b32_e32 v49, v54
	v_mov_b32_e32 v51, v54
	v_mov_b32_e32 v86, v56
	v_mov_b32_e32 v87, v17
	v_mov_b32_e32 v54, v53
	v_mov_b32_e32 v48, v53
	v_mov_b32_e32 v20, v52
	v_mov_b32_e32 v21, v57
	v_mov_b32_e32 v50, v16
	v_pk_mul_f32 v[86:87], v[86:87], v[54:55]
	v_mov_b32_e32 v53, v55
	v_pk_fma_f32 v[20:21], v[20:21], v[50:51], v[86:87] neg_lo:[0,0,1] neg_hi:[0,0,1]
	v_pk_mul_f32 v[50:51], v[52:53], v[56:57]
	v_mov_b32_e32 v78, v45
	v_pk_fma_f32 v[16:17], v[16:17], v[48:49], v[50:51]
	v_and_b32_e32 v49, 0xffff0000, v18
	v_lshlrev_b32_e32 v48, 16, v22
	v_pk_mul_f32 v[48:49], v[58:59], v[48:49] op_sel_hi:[0,1]
	v_mov_b32_e32 v50, v40
	v_mov_b32_e32 v51, v33
	v_pk_mul_f32 v[48:49], v[50:51], v[48:49]
	v_and_b32_e32 v51, 0xffff0000, v22
	v_lshlrev_b32_e32 v50, 16, v18
	v_pk_mul_f32 v[50:51], v[58:59], v[50:51] op_sel_hi:[0,1]
	v_mov_b32_e32 v33, v41
	v_mov_b32_e32 v79, v46
	v_pk_mul_f32 v[32:33], v[32:33], v[50:51]
	v_mov_b32_e32 v51, v46
	v_mov_b32_e32 v46, v45
	v_mov_b32_e32 v45, v47
	v_mov_b32_e32 v50, v44
	v_pk_mul_f32 v[44:45], v[48:49], v[44:45]
	v_mov_b32_e32 v40, v32
	v_mov_b32_e32 v52, v48
	v_mov_b32_e32 v53, v33
	v_pk_fma_f32 v[32:33], v[32:33], v[78:79], v[44:45]
	v_and_b32_e32 v45, 0xffff0000, v19
	v_lshlrev_b32_e32 v44, 16, v23
	v_and_b32_e32 v23, 0xffff0000, v23
	v_lshlrev_b32_e32 v22, 16, v19
	v_pk_mul_f32 v[52:53], v[52:53], v[46:47]
	v_pk_mul_f32 v[44:45], v[58:59], v[44:45] op_sel_hi:[0,1]
	v_mov_b32_e32 v46, v42
	v_mov_b32_e32 v47, v35
	v_pk_mul_f32 v[18:19], v[58:59], v[22:23] op_sel_hi:[0,1]
	v_mov_b32_e32 v35, v43
	v_pk_mul_f32 v[44:45], v[46:47], v[44:45]
	v_pk_mul_f32 v[18:19], v[34:35], v[18:19]
	v_mov_b32_e32 v81, v38
	v_mov_b32_e32 v35, v38
	v_mov_b32_e32 v42, v44
	v_mov_b32_e32 v43, v19
	v_mov_b32_e32 v38, v37
	v_mov_b32_e32 v22, v18
	v_mov_b32_e32 v23, v45
	v_mov_b32_e32 v34, v36
	v_pk_mul_f32 v[42:43], v[42:43], v[38:39]
	v_mov_b32_e32 v80, v37
	v_pk_fma_f32 v[22:23], v[22:23], v[34:35], v[42:43] neg_lo:[0,0,1] neg_hi:[0,0,1]
	v_mov_b32_e32 v37, v39
	v_cvt_pk_bf16_f32 v135, v22, v23
	v_pk_mul_f32 v[34:35], v[44:45], v[36:37]
	v_cvt_pk_bf16_f32 v130, v32, v33
	v_pk_fma_f32 v[18:19], v[18:19], v[80:81], v[34:35]
	v_mov_b32_e32 v41, v49
	v_cvt_pk_bf16_f32 v131, v18, v19
	v_cvt_pk_bf16_f32 v133, v20, v21
	s_waitcnt lgkmcnt(0)
	v_and_b32_e32 v23, 0xffff0000, v4
	v_lshlrev_b32_e32 v22, 16, v8
	v_pk_mul_f32 v[22:23], v[58:59], v[22:23] op_sel_hi:[0,1]
	s_waitcnt vmcnt(7)
	v_mov_b32_e32 v20, v63
	s_waitcnt vmcnt(6)
	v_mov_b32_e32 v18, v67
	v_mov_b32_e32 v19, v68
	s_waitcnt vmcnt(2)
	v_mov_b32_e32 v32, v70
	v_mov_b32_e32 v37, v68
	s_waitcnt vmcnt(0)
	v_mov_b32_e32 v33, v75
	v_pk_mul_f32 v[22:23], v[32:33], v[22:23]
	v_and_b32_e32 v33, 0xffff0000, v8
	v_lshlrev_b32_e32 v32, 16, v4
	v_pk_mul_f32 v[32:33], v[58:59], v[32:33] op_sel_hi:[0,1]
	v_mov_b32_e32 v75, v71
	v_mov_b32_e32 v68, v67
	v_mov_b32_e32 v67, v69
	v_pk_mul_f32 v[32:33], v[74:75], v[32:33]
	v_mov_b32_e32 v35, v23
	v_mov_b32_e32 v38, v22
	v_pk_mul_f32 v[22:23], v[22:23], v[66:67]
	v_lshlrev_b32_e32 v8, 16, v5
	v_pk_fma_f32 v[48:49], v[32:33], v[18:19], v[22:23]
	v_and_b32_e32 v19, 0xffff0000, v5
	v_lshlrev_b32_e32 v18, 16, v9
	v_pk_mul_f32 v[18:19], v[58:59], v[18:19] op_sel_hi:[0,1]
	v_mov_b32_e32 v22, v72
	v_mov_b32_e32 v23, v77
	v_and_b32_e32 v9, 0xffff0000, v9
	v_mov_b32_e32 v21, v64
	v_pk_mul_f32 v[18:19], v[18:19], v[22:23]
	v_pk_mul_f32 v[4:5], v[58:59], v[8:9] op_sel_hi:[0,1]
	v_mov_b32_e32 v77, v73
	v_mov_b32_e32 v23, v64
	v_mov_b32_e32 v64, v63
	v_mov_b32_e32 v63, v65
	v_mov_b32_e32 v34, v32
	v_pk_mul_f32 v[4:5], v[4:5], v[76:77]
	v_mov_b32_e32 v9, v19
	v_mov_b32_e32 v32, v18
	v_pk_mul_f32 v[18:19], v[18:19], v[62:63]
	v_mov_b32_e32 v39, v33
	v_mov_b32_e32 v8, v4
	v_mov_b32_e32 v33, v5
	v_pk_fma_f32 v[4:5], v[4:5], v[20:21], v[18:19]
	v_and_b32_e32 v19, 0xffff0000, v6
	v_lshlrev_b32_e32 v18, 16, v10
	v_pk_mul_f32 v[18:19], v[58:59], v[18:19] op_sel_hi:[0,1]
	v_mov_b32_e32 v20, v24
	v_mov_b32_e32 v21, v29
	v_pk_fma_f32 v[40:41], v[40:41], v[50:51], v[52:53] neg_lo:[0,0,1] neg_hi:[0,0,1]
	v_pk_mul_f32 v[50:51], v[18:19], v[20:21]
	v_and_b32_e32 v19, 0xffff0000, v10
	v_lshlrev_b32_e32 v18, 16, v6
	v_pk_mul_f32 v[18:19], v[58:59], v[18:19] op_sel_hi:[0,1]
	v_mov_b32_e32 v29, v25
	v_pk_mul_f32 v[28:29], v[18:19], v[28:29]
	v_mul_hi_i32 v19, v59, s34
	v_lshrrev_b32_e32 v20, 31, v19
	v_ashrrev_i32_e32 v19, 2, v19
	v_add_u32_e32 v74, v19, v20
	v_add_u32_e32 v10, 0x200, v59
	v_mul_lo_u32 v19, v74, 24
	v_sub_u32_e32 v75, v59, v19
	v_mul_hi_i32 v19, v10, s34
	v_lshrrev_b32_e32 v20, 31, v19
	v_ashrrev_i32_e32 v19, 2, v19
	v_add_u32_e32 v76, v19, v20
	v_add_u32_e32 v18, 0x400, v59
	v_mul_lo_u32 v19, v76, 24
	v_ashrrev_i32_e32 v56, 4, v59
	v_sub_u32_e32 v77, v10, v19
	v_mul_hi_i32 v10, v18, s34
	v_mov_b32_e32 v22, v62
	v_add_u32_e32 v62, 32, v56
	v_lshrrev_b32_e32 v19, 31, v10
	v_ashrrev_i32_e32 v10, 2, v10
	v_pk_mul_f32 v[32:33], v[32:33], v[64:65]
	v_lshlrev_b32_e32 v61, 3, v59
	v_add_u32_e32 v78, v10, v19
	v_ashrrev_i32_e32 v57, 31, v56
	v_ashrrev_i32_e32 v63, 31, v62
	v_pk_fma_f32 v[8:9], v[8:9], v[22:23], v[32:33] neg_lo:[0,0,1] neg_hi:[0,0,1]
	v_and_b32_e32 v6, 0x78, v61
	v_mul_lo_u32 v10, v78, 24
	v_lshlrev_b64 v[64:65], 8, v[56:57]
	v_lshlrev_b64 v[22:23], 8, v[62:63]
	v_mov_b32_e32 v36, v66
	v_pk_mul_f32 v[38:39], v[38:39], v[68:69]
	v_sub_u32_e32 v79, v18, v10
	v_lshl_add_u64 v[18:19], s[6:7], 0, v[64:65]
	v_lshlrev_b32_e32 v20, 1, v6
	v_mov_b32_e32 v21, v165
	v_lshl_add_u64 v[22:23], s[6:7], 0, v[22:23]
	v_pk_fma_f32 v[46:47], v[34:35], v[36:37], v[38:39] neg_lo:[0,0,1] neg_hi:[0,0,1]
	v_lshl_add_u64 v[18:19], v[18:19], 0, v[20:21]
	v_lshl_add_u64 v[22:23], v[22:23], 0, v[20:21]
	v_lshlrev_b32_e32 v34, 3, v75
	v_cvt_pk_bf16_f32 v134, v40, v41
	global_load_dwordx4 v[18:21], v[18:19], off
	s_nop 0
	global_load_dwordx4 v[22:25], v[22:23], off
	v_mov_b64_e32 v[40:41], s[4:5]
	v_ashrrev_i32_e32 v35, 31, v34
	v_mad_i64_i32 v[32:33], s[0:1], v74, s30, v[40:41]
	v_lshlrev_b64 v[66:67], 1, v[34:35]
	v_lshl_add_u64 v[32:33], v[32:33], 0, v[66:67]
	v_lshlrev_b32_e32 v38, 3, v77
	global_load_dwordx4 v[32:35], v[32:33], off
	v_ashrrev_i32_e32 v39, 31, v38
	v_mad_i64_i32 v[36:37], s[0:1], v76, s30, v[40:41]
	v_lshlrev_b64 v[68:69], 1, v[38:39]
	v_lshl_add_u64 v[36:37], v[36:37], 0, v[68:69]
	v_lshlrev_b32_e32 v42, 3, v79
	global_load_dwordx4 v[36:39], v[36:37], off
	v_ashrrev_i32_e32 v43, 31, v42
	v_mad_i64_i32 v[40:41], s[0:1], v78, s30, v[40:41]
	v_lshlrev_b64 v[70:71], 1, v[42:43]
	v_lshl_add_u64 v[40:41], v[40:41], 0, v[70:71]
	global_load_dwordx4 v[40:43], v[40:41], off
	v_mov_b32_e32 v44, v13
	v_mov_b32_e32 v45, v14
	v_mov_b32_e32 v55, v14
	v_mov_b32_e32 v72, v50
	v_mov_b32_e32 v73, v29
	v_mov_b32_e32 v14, v13
	v_mov_b32_e32 v13, v15
	v_mov_b32_e32 v54, v12
	v_pk_mul_f32 v[72:73], v[72:73], v[14:15]
	v_pk_mul_f32 v[12:13], v[50:51], v[12:13]
	v_and_b32_e32 v15, 0xffff0000, v7
	v_lshlrev_b32_e32 v14, 16, v11
	v_mov_b32_e32 v52, v28
	v_pk_fma_f32 v[12:13], v[28:29], v[44:45], v[12:13]
	v_pk_mul_f32 v[14:15], v[58:59], v[14:15] op_sel_hi:[0,1]
	v_mov_b32_e32 v28, v26
	v_mov_b32_e32 v29, v31
	v_and_b32_e32 v11, 0xffff0000, v11
	v_lshlrev_b32_e32 v10, 16, v7
	v_cvt_pk_bf16_f32 v129, v16, v17
	v_mov_b32_e32 v16, v1
	v_mov_b32_e32 v17, v2
	v_pk_mul_f32 v[14:15], v[14:15], v[28:29]
	v_pk_mul_f32 v[6:7], v[58:59], v[10:11] op_sel_hi:[0,1]
	v_mov_b32_e32 v31, v27
	v_mov_b32_e32 v27, v2
	v_mov_b32_e32 v2, v1
	v_mov_b32_e32 v1, v3
	v_pk_mul_f32 v[6:7], v[6:7], v[30:31]
	v_mov_b32_e32 v26, v0
	v_pk_mul_f32 v[0:1], v[14:15], v[0:1]
	v_mov_b32_e32 v28, v14
	v_pk_fma_f32 v[0:1], v[6:7], v[16:17], v[0:1]
	v_mov_b32_e32 v29, v7
	v_cvt_pk_bf16_f32 v139, v0, v1
	v_and_b32_e32 v0, 0xfffff0, v56
	v_lshlrev_b32_e32 v1, 1, v56
	v_and_or_b32 v0, v1, 8, v0
	v_pk_mul_f32 v[28:29], v[28:29], v[2:3]
	v_lshrrev_b32_e32 v1, 1, v56
	v_lshrrev_b32_e32 v0, 1, v0
	v_bfe_u32 v2, v61, 5, 2
	v_and_b32_e32 v3, 3, v56
	v_or_b32_e32 v0, v0, v2
	v_and_or_b32 v1, v1, 4, v3
	v_lshlrev_b32_e32 v3, 4, v59
	v_cvt_pk_bf16_f32 v137, v4, v5
	v_lshlrev_b32_e32 v0, 9, v0
	v_lshlrev_b32_e32 v1, 6, v1
	v_and_b32_e32 v4, 48, v3
	v_or3_b32 v196, v0, v1, v4
	v_and_b32_e32 v0, 0xfffff0, v62
	v_lshlrev_b32_e32 v5, 1, v62
	v_and_or_b32 v0, v5, 8, v0
	v_lshrrev_b32_e32 v0, 1, v0
	v_or_b32_e32 v0, v0, v2
	v_lshlrev_b32_e32 v0, 9, v0
	v_or3_b32 v198, v0, v1, v4
	v_add_u32_e32 v0, 16, v196
	s_waitcnt vmcnt(4)
	ds_write_b128 v0, v[18:21]
	v_add_u32_e32 v0, 16, v198
	s_waitcnt vmcnt(3)
	ds_write_b128 v0, v[22:25]
	v_mul_lo_u32 v0, v74, s30
	v_bitop3_b32 v1, v74, v75, 7 bitop3:0x6c
	v_lshl_add_u32 v200, v1, 4, v0
	v_add_u32_e32 v0, 16, v200
	s_waitcnt vmcnt(2)
	ds_write_b128 v0, v[32:35] offset:32768
	v_mul_lo_u32 v0, v76, s30
	v_bitop3_b32 v1, v76, v77, 7 bitop3:0x6c
	v_lshl_add_u32 v201, v1, 4, v0
	v_add_u32_e32 v0, 16, v201
	v_bitop3_b32 v1, v78, v79, 7 bitop3:0x6c
	v_and_b32_e32 v2, 0xc0, v3
	s_waitcnt vmcnt(1)
	ds_write_b128 v0, v[36:39] offset:32768
	v_mul_lo_u32 v0, v78, s30
	v_lshl_add_u32 v205, v1, 4, v0
	v_add_u32_e32 v0, 16, v205
	v_and_b32_e32 v1, 0x118, v61
	s_cselect_b32 s0, 16, 0
	s_waitcnt vmcnt(0)
	ds_write_b128 v0, v[40:43] offset:32768
	v_lshlrev_b32_e32 v0, 1, v59
	v_and_or_b32 v0, v0, 32, v1
	v_add3_u32 v185, v2, s0, v0
	s_mul_i32 s0, s22, 0x78000
	s_mul_hi_i32 s1, s22, 0x78000
	s_add_u32 s0, s0, 0xf006000
	s_addc_u32 s1, s1, 0
	v_mov_b64_e32 v[0:1], s[0:1]
	v_and_b32_e32 v4, 0x70, v3
	v_bitop3_b32 v206, v166, v3, s36 bitop3:0x78
	v_mad_i64_i32 v[2:3], s[0:1], v78, s30, v[0:1]
	v_mov_b32_e32 v53, v51
	v_mov_b32_e32 v10, v6
	v_mov_b32_e32 v11, v15
	v_lshl_add_u64 v[170:171], v[2:3], 0, v[70:71]
	v_mad_i64_i32 v[2:3], s[0:1], v76, s30, v[0:1]
	v_mad_i64_i32 v[0:1], s[0:1], v74, s30, v[0:1]
	v_pk_fma_f32 v[52:53], v[52:53], v[54:55], v[72:73] neg_lo:[0,0,1] neg_hi:[0,0,1]
	v_pk_fma_f32 v[10:11], v[10:11], v[26:27], v[28:29] neg_lo:[0,0,1] neg_hi:[0,0,1]
	v_lshl_add_u64 v[174:175], v[0:1], 0, v[66:67]
	v_mad_i64_i32 v[176:177], s[0:1], s22, v182, v[64:65]
	v_and_b32_e32 v0, 15, v59
	v_mov_b32_e32 v14, v165
	v_mov_b32_e32 v15, v165
	v_cvt_pk_bf16_f32 v140, v46, v47
	v_cvt_pk_bf16_f32 v141, v8, v9
	v_cvt_pk_bf16_f32 v142, v52, v53
	v_cvt_pk_bf16_f32 v143, v10, v11
	v_cvt_pk_bf16_f32 v136, v48, v49
	v_cvt_pk_bf16_f32 v138, v12, v13
	v_bitop3_b32 v203, v166, v4, 32 bitop3:0x36
	v_bitop3_b32 v202, v166, v4, 64 bitop3:0x36
	v_bitop3_b32 v199, v166, v4, s37 bitop3:0x36
	v_bitop3_b32 v197, v166, v4, s38 bitop3:0x36
	v_bitop3_b32 v195, v166, v4, s39 bitop3:0x36
	v_bitop3_b32 v194, v166, v4, s35 bitop3:0x36
	v_bitop3_b32 v193, v166, v4, s40 bitop3:0x36
	v_bitop3_b32 v192, v166, v4, s41 bitop3:0x36
	v_bitop3_b32 v191, v166, v4, s42 bitop3:0x36
	v_bitop3_b32 v190, v166, v4, s43 bitop3:0x36
	v_bitop3_b32 v189, v166, v4, s44 bitop3:0x36
	v_cmp_gt_u32_e64 s[4:5], 32, v60
	v_lshl_add_u64 v[172:173], v[2:3], 0, v[68:69]
	v_lshl_or_b32 v176, v0, 4, v176
	v_mov_b32_e32 v0, v165
	v_mov_b32_e32 v1, v165
	v_mov_b32_e32 v2, v165
	v_mov_b32_e32 v3, v165
	v_mov_b32_e32 v4, v165
	v_mov_b32_e32 v5, v165
	v_mov_b32_e32 v6, v165
	v_mov_b32_e32 v7, v165
	v_mov_b32_e32 v8, v165
	v_mov_b32_e32 v9, v165
	v_mov_b32_e32 v10, v165
	v_mov_b32_e32 v11, v165
	v_mov_b32_e32 v12, v165
	v_mov_b32_e32 v13, v165
	v_mov_b64_e32 v[30:31], v[14:15]
	v_mov_b64_e32 v[46:47], v[14:15]
	v_mov_b64_e32 v[62:63], v[14:15]
	v_cvt_pk_bf16_f32 v132, v82, v83
	v_cvt_pk_bf16_f32 v128, v84, v85
	v_mov_b64_e32 v[28:29], v[12:13]
	v_mov_b64_e32 v[26:27], v[10:11]
	v_mov_b64_e32 v[24:25], v[8:9]
	v_mov_b64_e32 v[22:23], v[6:7]
	v_mov_b64_e32 v[20:21], v[4:5]
	v_mov_b64_e32 v[18:19], v[2:3]
	v_mov_b64_e32 v[16:17], v[0:1]
	v_mov_b64_e32 v[44:45], v[12:13]
	v_mov_b64_e32 v[42:43], v[10:11]
	v_mov_b64_e32 v[40:41], v[8:9]
	v_mov_b64_e32 v[38:39], v[6:7]
	v_mov_b64_e32 v[36:37], v[4:5]
	v_mov_b64_e32 v[34:35], v[2:3]
	v_mov_b64_e32 v[32:33], v[0:1]
	v_mov_b64_e32 v[60:61], v[12:13]
	v_mov_b64_e32 v[58:59], v[10:11]
	v_mov_b64_e32 v[56:57], v[8:9]
	v_mov_b64_e32 v[54:55], v[6:7]
	v_mov_b64_e32 v[52:53], v[4:5]
	v_mov_b64_e32 v[50:51], v[2:3]
	v_mov_b64_e32 v[48:49], v[0:1]
